# attention P.V: next group's transposed V-fragment reads issued before the current group's MFMAs (counted lgkmcnt, own registers)
# speedup vs baseline: 1.0035x; 1.0035x over previous
; #define LAS __attribute__((address_space(3)))
; #define MFMA16(a, b, c) __builtin_amdgcn_mfma_f32_16x16x32_bf16((a), (b), (c), 0, 0, 0)
; __device__ __forceinline__ void attn_phase(Frame& F, bf16* OZ) {
;     ...
;             const int spos0 = !smp ? (2 * qb + 1 - kb) * 64 : (kb == 0 ? 1024 : 1024 - 64 * kb), nvalid = (smp && kb == 0) ? 16 : 64;
;             if (kb > 0) { ATT_LOAD_KV(kb); __syncthreads(); }
;             bool done = true;
;             const bool none_visible = spos0 > __builtin_amdgcn_readfirstlane(tpos - l15) + 14;
;             if (active && none_visible) done = false;
;             if (active && !none_visible) {
;                 f32x4 sc[4];
; #pragma unroll
;                 for (int sb = 0; sb < 4; ++sb) { sc[sb] = (f32x4){0.f, 0.f, 0.f, 0.f};
; #pragma unroll
;                     for (int ks = 0; ks < 4; ++ks) { const bf16x8 a = *(const LAS bf16x8*)(L + KS + (16 * sb + l15) * ST_ + (32 * ks + 8 * g4) * 2); sc[sb] = MFMA16(a, qf[ks], sc[sb]); } }
;                 float lk[4][4], tsum[4], above[4], ttot[4];
; #pragma unroll
;                 for (int sb = 0; sb < 4; ++sb) { tsum[sb] = 0.f;
; #pragma unroll
;                     for (int e = 0; e < 4; ++e) { const int s = 16 * sb + 4 * g4 + e; const float z = sc[sb][e]; const bool vis = (s < nvalid) && (spos0 + s < tpos);
;                         const float sp = fmaxf(z, 0.f) + __logf(1.0f + __expf(-fabsf(z)));
;                         lk[sb][e] = vis ? -sp : 0.f; sc[sb][e] = vis ? z - sp : -1e30f; tsum[sb] += lk[sb][e]; }
.LBB0_1910:
	s_add_i32 s1, s60, s21
	s_and_b64 s[18:19], s[38:39], exec
	s_cselect_b32 s18, s0, s1
	v_readfirstlane_b32 s0, v150
	s_add_i32 s0, s0, 14
	s_cmp_gt_i32 s18, s0
	s_cselect_b64 s[0:1], -1, 0
	s_andn2_b64 s[0:1], s[0:1], s[64:65]
	s_or_b64 s[24:25], s[42:43], s[0:1]
	s_or_b64 s[24:25], s[24:25], s[64:65]
	s_and_b64 vcc, exec, s[24:25]
	s_waitcnt vmcnt(3)
	ds_write_b128 v144, v[58:61] offset:34816
	s_waitcnt vmcnt(2)
	ds_write_b128 v144, v[62:65] offset:52224
	s_waitcnt vmcnt(1)
	ds_write_b128 v145, v[66:69] offset:34816
	s_waitcnt vmcnt(0)
	ds_write_b128 v145, v[70:73] offset:52224
	s_waitcnt lgkmcnt(0)
	s_barrier
	s_cbranch_vccnz .LBB0_1912
	ds_read_b128 v[58:61], v146 offset:34816
	ds_read_b128 v[62:65], v146 offset:34880
	ds_read_b128 v[66:69], v146 offset:39168
	ds_read_b128 v[70:73], v146 offset:39232
	ds_read_b128 v[94:97], v146 offset:34944
	v_and_b32_e32 v5, 64, v147
	s_waitcnt lgkmcnt(4)
	v_mfma_f32_16x16x32_bf16 v[58:61], v[58:61], v[10:13], 0
	v_xor_b32_e32 v4, 16, v147
	v_add_u32_e32 v5, 64, v5
	v_cmp_lt_i32_e32 vcc, v4, v5
	s_waitcnt lgkmcnt(3)
	v_mfma_f32_16x16x32_bf16 v[58:61], v[62:65], v[14:17], v[58:61]
	ds_read_b128 v[62:65], v146 offset:35008
	ds_read_b128 v[154:157], v146 offset:39296
	ds_read_b128 v[158:161], v146 offset:39360
	v_cndmask_b32_e32 v4, v147, v4, vcc
	s_waitcnt lgkmcnt(5)
	v_mfma_f32_16x16x32_bf16 v[66:69], v[66:69], v[10:13], 0
	s_waitcnt lgkmcnt(3)
	v_mfma_f32_16x16x32_bf16 v[58:61], v[94:97], v[18:21], v[58:61]
	ds_read_b128 v[94:97], v146 offset:43520
	ds_read_b128 v[162:165], v146 offset:43584
	ds_read_b128 v[166:169], v146 offset:43648
	ds_read_b128 v[170:173], v146 offset:43712
	ds_read_b128 v[174:177], v146 offset:47872
	ds_read_b128 v[178:181], v146 offset:47936
	ds_read_b128 v[184:187], v146 offset:48000
	ds_read_b128 v[188:191], v146 offset:48064
	s_waitcnt lgkmcnt(10)
	v_mfma_f32_16x16x32_bf16 v[62:65], v[62:65], v[22:25], v[58:61]
	v_mfma_f32_16x16x32_bf16 v[58:61], v[70:73], v[14:17], v[66:69]
	s_waitcnt lgkmcnt(9)
	v_mfma_f32_16x16x32_bf16 v[58:61], v[154:157], v[18:21], v[58:61]
	v_lshlrev_b32_e32 v156, 2, v4
	v_xor_b32_e32 v4, 32, v147
	v_cmp_lt_i32_e32 vcc, v4, v5
	s_waitcnt lgkmcnt(8)
	v_mfma_f32_16x16x32_bf16 v[58:61], v[158:161], v[22:25], v[58:61]
	v_or_b32_e32 v158, s18, v1
	v_cndmask_b32_e32 v4, v147, v4, vcc
	v_lshlrev_b32_e32 v154, 2, v4
	v_xor_b32_e32 v4, 48, v147
	v_cmp_lt_i32_e32 vcc, v4, v5
	s_waitcnt lgkmcnt(7)
	v_mfma_f32_16x16x32_bf16 v[66:69], v[94:97], v[10:13], 0
	v_or_b32_e32 v159, s18, v86
	v_cndmask_b32_e32 v4, v147, v4, vcc
	v_lshlrev_b32_e32 v155, 2, v4
	v_mul_f32_e64 v4, |v62|, s49
	v_exp_f32_e32 v4, v4
	s_waitcnt lgkmcnt(6)
	v_mfma_f32_16x16x32_bf16 v[66:69], v[162:165], v[14:17], v[66:69]
	v_or_b32_e32 v162, s18, v88
	v_add_f32_e32 v4, 1.0, v4
	s_waitcnt lgkmcnt(5)
	v_mfma_f32_16x16x32_bf16 v[66:69], v[166:169], v[18:21], v[66:69]
	v_log_f32_e32 v4, v4
	v_max_f32_e32 v5, v62, v62
	v_max_f32_e32 v5, 0, v5
	s_waitcnt lgkmcnt(4)
	v_mfma_f32_16x16x32_bf16 v[70:73], v[170:173], v[22:25], v[66:69]
	v_mul_f32_e32 v92, 0x3f317217, v4
	v_fma_f32 v92, v4, s53, -v92
	v_fmac_f32_e32 v92, 0x3377d1cf, v4
	v_fma_f32 v4, v4, s53, v92
	s_waitcnt lgkmcnt(3)
	v_mfma_f32_16x16x32_bf16 v[66:69], v[174:177], v[10:13], 0
	v_mul_f32_e64 v92, |v63|, s49
	v_exp_f32_e32 v92, v92
	v_add_f32_e32 v4, v5, v4
	v_sub_f32_e32 v161, v62, v4
	v_sub_f32_e32 v160, 0, v4
	v_add_f32_e32 v4, 1.0, v92
	v_max_f32_e32 v62, v63, v63
	v_max_f32_e32 v62, 0, v62
	v_log_f32_e32 v4, v4
	v_or_b32_e32 v5, s18, v98
	s_waitcnt lgkmcnt(2)
	v_mfma_f32_16x16x32_bf16 v[66:69], v[178:181], v[14:17], v[66:69]
	v_mul_f32_e32 v92, 0x3f317217, v4
	v_fma_f32 v92, v4, s53, -v92
	v_fmac_f32_e32 v92, 0x3377d1cf, v4
	v_fma_f32 v4, v4, s53, v92
	s_waitcnt lgkmcnt(1)
	v_mfma_f32_16x16x32_bf16 v[66:69], v[184:187], v[18:21], v[66:69]
	v_cmp_lt_i32_e32 vcc, v5, v90
	v_mul_f32_e64 v5, |v64|, s49
	v_exp_f32_e32 v5, v5
	v_add_f32_e32 v62, v62, v4
	v_cndmask_b32_e64 v4, 0, -v62, vcc
	v_sub_f32_e32 v62, v63, v62
	v_add_f32_e32 v5, 1.0, v5
	v_cndmask_b32_e32 v157, v149, v62, vcc
	v_mul_f32_e64 v92, |v65|, s49
	v_exp_f32_e32 v92, v92
	v_log_f32_e32 v5, v5
	v_max_f32_e32 v62, v64, v64
	v_max_f32_e32 v94, 0, v62
	s_waitcnt lgkmcnt(0)
	v_mfma_f32_16x16x32_bf16 v[66:69], v[188:191], v[22:25], v[66:69]
	v_mul_f32_e32 v62, 0x3f317217, v5
	v_fma_f32 v62, v5, s53, -v62
	v_fmac_f32_e32 v62, 0x3377d1cf, v5
	v_fma_f32 v5, v5, s53, v62
	v_or_b32_e32 v63, s18, v75
	s_nop 0
	v_mov_b32_e32 v96, v5
	v_add_f32_e32 v5, 1.0, v92
	v_max_f32_e32 v92, v65, v65
	v_max_f32_e32 v92, 0, v92
	v_log_f32_e32 v5, v5
	v_or_b32_e32 v62, s18, v99
	v_mul_f32_e32 v95, 0x3f317217, v5
	v_fma_f32 v95, v5, s53, -v95
	v_fmac_f32_e32 v95, 0x3377d1cf, v5
	v_fma_f32 v5, v5, s53, v95
	s_nop 1
	v_add_f32_e32 v5, v92, v5
	v_mul_f32_e64 v92, |v58|, s49
	v_exp_f32_e32 v92, v92
	v_cmp_lt_i32_e32 vcc, v62, v90
	v_max_f32_e32 v95, v58, v58
	v_max_f32_e32 v95, 0, v95
	v_cndmask_b32_e64 v62, 0, -v5, vcc
	v_sub_f32_e32 v5, v65, v5
	v_cndmask_b32_e32 v65, v149, v5, vcc
	v_add_f32_e32 v5, 1.0, v92
	s_nop 1
	v_log_f32_e32 v5, v5
	v_or_b32_e32 v92, s18, v100
	v_mul_f32_e32 v97, 0x3f317217, v5
	v_fma_f32 v97, v5, s53, -v97
	v_fmac_f32_e32 v97, 0x3377d1cf, v5
	v_fma_f32 v5, v5, s53, v97
	s_nop 1
	v_add_f32_e32 v5, v95, v5
	v_mul_f32_e64 v95, |v59|, s49
	v_exp_f32_e32 v95, v95
	v_sub_f32_e32 v58, v58, v5
	v_cmp_lt_i32_e32 vcc, v92, v90
	v_sub_f32_e32 v5, 0, v5
	s_nop 0
	v_cndmask_b32_e32 v163, v149, v58, vcc
	v_add_f32_e32 v58, 1.0, v95
	v_cndmask_b32_e32 v5, 0, v5, vcc
	v_max_f32_e32 v95, v59, v59
	v_max_f32_e32 v95, 0, v95
	v_log_f32_e32 v58, v58
	v_or_b32_e32 v92, s18, v101
; __device__ __forceinline__ void attn_phase(Frame& F, bf16* OZ) {
;     ...
;                 for (int sb = 0; sb < 4; ++sb) { tsum[sb] = 0.f;
; #pragma unroll
;                     for (int e = 0; e < 4; ++e) { const int s = 16 * sb + 4 * g4 + e; const float z = sc[sb][e]; const bool vis = (s < nvalid) && (spos0 + s < tpos);
;                         const float sp = fmaxf(z, 0.f) + __logf(1.0f + __expf(-fabsf(z)));
;                         lk[sb][e] = vis ? -sp : 0.f; sc[sb][e] = vis ? z - sp : -1e30f; tsum[sb] += lk[sb][e]; }
;                     const float v1 = __shfl_xor(tsum[sb], 16), v2 = __shfl_xor(tsum[sb], 32), v3 = __shfl_xor(tsum[sb], 48);
;                     above[sb] = ((g4 ^ 1) > g4 ? v1 : 0.f) + ((g4 ^ 2) > g4 ? v2 : 0.f) + ((g4 ^ 3) > g4 ? v3 : 0.f);
;                     ttot[sb] = (tsum[sb] + v1) + (v2 + v3); }
	v_mul_f32_e32 v97, 0x3f317217, v58
	v_fma_f32 v97, v58, s53, -v97
	v_fmac_f32_e32 v97, 0x3377d1cf, v58
	v_fma_f32 v58, v58, s53, v97
	s_nop 1
	v_add_f32_e32 v58, v95, v58
	v_mul_f32_e64 v95, |v60|, s49
	v_exp_f32_e32 v95, v95
	v_cmp_lt_i32_e32 vcc, v92, v90
	s_nop 1
	v_cndmask_b32_e64 v166, 0, -v58, vcc
	v_sub_f32_e32 v58, v59, v58
	v_cndmask_b32_e32 v167, v149, v58, vcc
	v_add_f32_e32 v58, 1.0, v95
	v_cmp_gt_f32_e32 vcc, s52, v58
	v_add_f32_e32 v5, v166, v5
	s_nop 0
	v_cndmask_b32_e64 v59, 0, 32, vcc
	v_ldexp_f32 v58, v58, v59
	v_log_f32_e32 v58, v58
	v_max_f32_e32 v59, v60, v60
	v_cndmask_b32_e32 v95, 0, v148, vcc
	v_max_f32_e32 v59, 0, v59
	v_mul_f32_e32 v92, 0x3f317217, v58
	v_fma_f32 v92, v58, s53, -v92
	v_fmac_f32_e32 v92, 0x3377d1cf, v58
	v_fmac_f32_e32 v92, 0x3f317217, v58
	v_cmp_lt_f32_e64 s[0:1], |v58|, s54
	s_nop 1
	v_cndmask_b32_e64 v58, v58, v92, s[0:1]
	v_mul_f32_e64 v92, |v61|, s49
	v_exp_f32_e32 v92, v92
	v_sub_f32_e32 v58, v58, v95
	v_add_f32_e32 v165, v59, v58
	v_sub_f32_e32 v168, v60, v165
	v_add_f32_e32 v58, 1.0, v92
	v_mul_f32_e64 v60, |v70|, s49
	v_exp_f32_e32 v60, v60
	v_log_f32_e32 v58, v58
	v_max_f32_e32 v59, v61, v61
	v_max_f32_e32 v95, 0, v59
	v_mul_f32_e32 v59, 0x3f317217, v58
	v_fma_f32 v59, v58, s53, -v59
	v_fmac_f32_e32 v59, 0x3377d1cf, v58
	v_fma_f32 v58, v58, s53, v59
	s_nop 1
	v_mov_b32_e32 v97, v58
	v_add_f32_e32 v58, 1.0, v60
	v_max_f32_e32 v60, v70, v70
	v_max_f32_e32 v60, 0, v60
	v_log_f32_e32 v58, v58
	v_or_b32_e32 v59, s18, v102
	v_mul_f32_e32 v92, 0x3f317217, v58
	v_fma_f32 v92, v58, s53, -v92
	v_fmac_f32_e32 v92, 0x3377d1cf, v58
	v_fma_f32 v58, v58, s53, v92
	s_nop 1
	v_add_f32_e32 v58, v60, v58
	v_sub_f32_e32 v60, v70, v58
	v_mul_f32_e64 v70, |v71|, s49
	v_exp_f32_e32 v70, v70
	v_cmp_lt_i32_e32 vcc, v59, v90
	v_sub_f32_e32 v58, 0, v58
	v_add_f32_e32 v59, 1.0, v70
	v_cndmask_b32_e32 v169, v149, v60, vcc
	v_cndmask_b32_e32 v58, 0, v58, vcc
	v_max_f32_e32 v70, v71, v71
	v_max_f32_e32 v70, 0, v70
	v_log_f32_e32 v59, v59
	v_or_b32_e32 v60, s18, v103
	v_mul_f32_e32 v92, 0x3f317217, v59
	v_fma_f32 v92, v59, s53, -v92
	v_fmac_f32_e32 v92, 0x3377d1cf, v59
	v_fma_f32 v59, v59, s53, v92
	s_nop 1
	v_cmp_lt_i32_e32 vcc, v60, v90
	v_mul_f32_e64 v60, |v72|, s49
	v_exp_f32_e32 v60, v60
	v_add_f32_e32 v59, v70, v59
	v_cndmask_b32_e64 v170, 0, -v59, vcc
	v_sub_f32_e32 v59, v71, v59
	v_cndmask_b32_e32 v171, v149, v59, vcc
	v_add_f32_e32 v59, 1.0, v60
	v_max_f32_e32 v70, v72, v72
	v_max_f32_e32 v70, 0, v70
	v_log_f32_e32 v59, v59
	v_or_b32_e32 v60, s18, v104
	v_add_f32_e32 v58, v170, v58
	v_mul_f32_e32 v71, 0x3f317217, v59
	v_fma_f32 v71, v59, s53, -v71
	v_fmac_f32_e32 v71, 0x3377d1cf, v59
	v_fma_f32 v59, v59, s53, v71
	s_nop 1
	v_cmp_lt_i32_e32 vcc, v60, v90
	v_mul_f32_e64 v60, |v73|, s49
	v_exp_f32_e32 v60, v60
	v_add_f32_e32 v59, v70, v59
	v_cndmask_b32_e64 v172, 0, -v59, vcc
	v_sub_f32_e32 v59, v72, v59
	v_cndmask_b32_e32 v173, v149, v59, vcc
	v_add_f32_e32 v59, 1.0, v60
	v_max_f32_e32 v70, v73, v73
	v_max_f32_e32 v70, 0, v70
	v_log_f32_e32 v59, v59
	v_or_b32_e32 v60, s18, v105
	v_add_f32_e32 v58, v172, v58
	v_mul_f32_e32 v71, 0x3f317217, v59
	v_fma_f32 v71, v59, s53, -v71
	v_fmac_f32_e32 v71, 0x3377d1cf, v59
	v_fma_f32 v59, v59, s53, v71
	s_nop 1
	v_add_f32_e32 v71, v70, v59
	v_cmp_lt_i32_e32 vcc, v60, v90
	v_sub_f32_e32 v60, v73, v71
	s_nop 0
	v_cndmask_b32_e64 v174, 0, -v71, vcc
	v_add_f32_e32 v58, v174, v58
	ds_bpermute_b32 v59, v154, v58
	ds_bpermute_b32 v70, v156, v58
	ds_bpermute_b32 v71, v155, v58
	v_cndmask_b32_e32 v175, v149, v60, vcc
	v_mul_f32_e64 v60, |v66|, s49
	v_exp_f32_e32 v60, v60
	s_waitcnt lgkmcnt(2)
	v_cndmask_b32_e64 v72, 0, v59, s[6:7]
	s_waitcnt lgkmcnt(0)
	v_pk_add_f32 v[58:59], v[58:59], v[70:71]
	v_cndmask_b32_e64 v92, 0, v71, s[8:9]
	v_pk_add_f32 v[58:59], v[58:59], v[58:59] op_sel_hi:[0,1]
	v_add_f32_e32 v58, 1.0, v60
	v_cndmask_b32_e64 v164, 0, v70, s[4:5]
	v_max_f32_e32 v70, v66, v66
	v_log_f32_e32 v58, v58
	v_max_f32_e32 v70, 0, v70
	v_or_b32_e32 v60, s18, v106
	v_mul_f32_e32 v71, 0x3f317217, v58
	v_fma_f32 v71, v58, s53, -v71
	v_fmac_f32_e32 v71, 0x3377d1cf, v58
	v_fma_f32 v58, v58, s53, v71
	s_nop 1
	v_add_f32_e32 v58, v70, v58
	v_mul_f32_e64 v70, |v67|, s49
	v_exp_f32_e32 v70, v70
	v_sub_f32_e32 v66, v66, v58
	v_cmp_lt_i32_e32 vcc, v60, v90
	v_sub_f32_e32 v58, 0, v58
	v_add_f32_e32 v60, 1.0, v70
	v_cndmask_b32_e32 v176, v149, v66, vcc
	v_cndmask_b32_e32 v58, 0, v58, vcc
	v_max_f32_e32 v70, v67, v67
	v_max_f32_e32 v70, 0, v70
	v_log_f32_e32 v60, v60
	v_or_b32_e32 v66, s18, v107
	v_mul_f32_e32 v71, 0x3f317217, v60
	v_fma_f32 v71, v60, s53, -v71
	v_fmac_f32_e32 v71, 0x3377d1cf, v60
	v_fma_f32 v60, v60, s53, v71
	s_nop 1
	v_cmp_lt_i32_e32 vcc, v66, v90
	v_mul_f32_e64 v66, |v68|, s49
	v_exp_f32_e32 v66, v66
	v_add_f32_e32 v60, v70, v60
	v_cndmask_b32_e64 v177, 0, -v60, vcc
	v_sub_f32_e32 v60, v67, v60
	v_add_f32_e32 v66, 1.0, v66
	v_cndmask_b32_e32 v60, v149, v60, vcc
	v_max_f32_e32 v70, v68, v68
	v_max_f32_e32 v70, 0, v70
	v_log_f32_e32 v66, v66
	v_or_b32_e32 v67, s18, v108
	v_add_f32_e32 v58, v177, v58
	v_mul_f32_e32 v71, 0x3f317217, v66
	v_fma_f32 v71, v66, s53, -v71
	v_fmac_f32_e32 v71, 0x3377d1cf, v66
	v_fma_f32 v66, v66, s53, v71
	s_nop 1
	v_cmp_lt_i32_e32 vcc, v67, v90
	v_mul_f32_e64 v67, |v69|, s49
	v_exp_f32_e32 v67, v67
	v_add_f32_e32 v66, v70, v66
	v_cndmask_b32_e64 v70, 0, -v66, vcc
	v_sub_f32_e32 v66, v68, v66
	v_cndmask_b32_e32 v71, v149, v66, vcc
	v_add_f32_e32 v66, 1.0, v67
	v_max_f32_e32 v68, v69, v69
	v_max_f32_e32 v68, 0, v68
	v_log_f32_e32 v66, v66
	v_or_b32_e32 v67, s18, v109
	v_add_f32_e32 v58, v70, v58
	v_cmp_lt_i32_e64 s[18:19], v158, v3
	v_mul_f32_e32 v73, 0x3f317217, v66
	v_fma_f32 v73, v66, s53, -v73
	v_fmac_f32_e32 v73, 0x3377d1cf, v66
	v_fma_f32 v66, v66, s53, v73
	s_nop 1
	v_add_f32_e32 v73, v68, v66
	v_cmp_lt_i32_e32 vcc, v67, v90
	v_cmp_lt_i32_e64 s[0:1], v162, v90
	s_nop 0
	v_cndmask_b32_e64 v178, 0, -v73, vcc
	v_add_f32_e32 v66, v178, v58
	ds_bpermute_b32 v67, v154, v66
	ds_bpermute_b32 v68, v156, v66
	v_sub_f32_e32 v58, v69, v73
	ds_bpermute_b32 v69, v155, v66
	v_cndmask_b32_e32 v58, v149, v58, vcc
	s_waitcnt lgkmcnt(2)
; __device__ __forceinline__ unsigned pk2(float lo, float hi) { const cvt_f2 v = {lo, hi}; const cvt_b2 r = __builtin_convertvector(v, cvt_b2); return __builtin_bit_cast(unsigned, r); }
; #define MFMA16(a, b, c) __builtin_amdgcn_mfma_f32_16x16x32_bf16((a), (b), (c), 0, 0, 0)
; __device__ __forceinline__ void attn_phase(Frame& F, bf16* OZ) {
;     ...
;                 float after = carry;
; #pragma unroll
;     ...
; #pragma unroll
;                     for (int e = 3; e >= 0; --e) { const float w = __expf(sc[sb][e] + run); run += lk[sb][e]; sc[sb][e] = w; }
;                     after += ttot[sb]; }
;                 carry = after;
; #pragma unroll
;                 for (int kk = 0; kk < 2; ++kk) { v4u pkd; pkd.x = pk2(sc[2 * kk][0], sc[2 * kk][1]); pkd.y = pk2(sc[2 * kk][2], sc[2 * kk][3]); pkd.z = pk2(sc[2 * kk + 1][0], sc[2 * kk + 1][1]); pkd.w = pk2(sc[2 * kk + 1][2], sc[2 * kk + 1][3]);
;                     const bf16x8 pf = __builtin_bit_cast(bf16x8, pkd);
; #pragma unroll
;                     for (int dh = 0; dh < 2; ++dh) { unsigned aa[4]; bf16x8 vf[4];
; #pragma unroll
;                         for (int i = 0; i < 4; ++i) aa[i] = F.lds0 + VS + (32 * kk + 4 * g4 + q) * ST_ + (32 * (2 * dh + (i >> 1)) + 8 * p + 4 * (i & 1)) * 2;
;                         tr_read_x4(aa, 16 * ST_, vf);
; #pragma unroll
;                         for (int i = 0; i < 4; ++i) oacc[4 * dh + i] = MFMA16(vf[i], pf, oacc[4 * dh + i]); } }
;                 done = __all(carry < ATT_THR);
	v_cndmask_b32_e64 v73, 0, v67, s[6:7]
	s_waitcnt lgkmcnt(1)
	v_cndmask_b32_e64 v179, 0, v68, s[4:5]
	v_add_f32_e32 v73, v179, v73
	s_waitcnt lgkmcnt(0)
	v_cndmask_b32_e64 v179, 0, v69, s[8:9]
	v_add_f32_e32 v73, v73, v179
	v_pk_add_f32 v[66:67], v[66:67], v[68:69]
	v_add_f32_e32 v68, v93, v73
	v_add_f32_e32 v58, v58, v68
	v_mul_f32_e32 v58, 0x3fb8aa3b, v58
	v_exp_f32_e32 v179, v58
	v_add_f32_e32 v58, v178, v68
	v_add_f32_e32 v68, v71, v58
	v_mul_f32_e32 v68, 0x3fb8aa3b, v68
	v_cmp_lt_i32_e32 vcc, v159, v90
	v_exp_f32_e32 v178, v68
	v_add_f32_e32 v180, v70, v58
	v_cndmask_b32_e32 v159, v149, v161, vcc
	v_pk_add_f32 v[68:69], v[94:95], v[96:97]
	v_cndmask_b32_e64 v71, 0, -v165, s[18:19]
	v_cndmask_b32_e32 v70, 0, v160, vcc
	v_cmp_lt_i32_e32 vcc, v63, v3
	v_pk_add_f32 v[94:95], v[70:71], v[4:5]
	v_cndmask_b32_e64 v96, 0, -v68, s[0:1]
	v_cndmask_b32_e64 v97, 0, -v69, vcc
	v_pk_add_f32 v[94:95], v[96:97], v[94:95]
	ds_bpermute_b32 v63, v156, v95
	v_mov_b32_e32 v165, v66
	v_mov_b32_e32 v73, v67
	v_add_f32_e32 v58, v60, v180
	v_pk_add_f32 v[66:67], v[164:165], v[72:73]
	v_mul_f32_e32 v58, 0x3fb8aa3b, v58
	v_pk_add_f32 v[66:67], v[66:67], v[92:93]
	ds_bpermute_b32 v92, v154, v95
	v_exp_f32_e32 v181, v58
	v_sub_f32_e32 v58, v64, v68
	s_waitcnt lgkmcnt(1)
	v_pk_add_f32 v[72:73], v[62:63], v[94:95]
	v_sub_f32_e32 v61, v61, v69
	ds_bpermute_b32 v69, v155, v95
	v_cndmask_b32_e64 v64, v149, v58, s[0:1]
	ds_bpermute_b32 v60, v156, v72
	ds_bpermute_b32 v58, v154, v72
	v_add_f32_e32 v5, v66, v67
	ds_bpermute_b32 v66, v155, v72
	v_cndmask_b32_e32 v93, v149, v61, vcc
	v_cndmask_b32_e64 v61, 0, v63, s[4:5]
	s_waitcnt lgkmcnt(4)
	v_cndmask_b32_e64 v63, 0, v92, s[6:7]
	v_add_f32_e32 v61, v61, v63
	s_waitcnt lgkmcnt(3)
	v_cndmask_b32_e64 v63, 0, v69, s[8:9]
	s_waitcnt lgkmcnt(2)
	v_cndmask_b32_e64 v68, 0, v60, s[4:5]
	s_waitcnt lgkmcnt(1)
	v_cndmask_b32_e64 v70, 0, v58, s[6:7]
	v_add_f32_e32 v63, v61, v63
	v_add_f32_e32 v61, v92, v69
	v_add_f32_e32 v68, v68, v70
	s_waitcnt lgkmcnt(0)
	v_cndmask_b32_e64 v70, 0, v66, s[8:9]
	v_pk_add_f32 v[60:61], v[72:73], v[60:61]
	v_pk_add_f32 v[58:59], v[58:59], v[66:67]
	v_add_f32_e32 v68, v68, v70
	v_pk_add_f32 v[154:155], v[60:61], v[58:59]
	v_add_f32_e32 v63, v63, v59
	v_add_f32_e32 v58, v68, v155
	v_cndmask_b32_e64 v70, v149, v168, s[18:19]
	v_add_f32_e32 v66, v93, v63
	v_add_f32_e32 v63, v97, v63
	v_add_f32_e32 v59, v65, v58
	v_add_f32_e32 v58, v62, v58
	v_add_f32_e32 v67, v70, v63
	v_add_f32_e32 v63, v71, v63
	v_add_f32_e32 v60, v64, v58
	v_add_f32_e32 v58, v96, v58
	v_add_f32_e32 v69, v167, v63
	v_add_f32_e32 v63, v166, v63
	v_add_f32_e32 v4, v4, v58
	v_add_f32_e32 v63, v163, v63
	v_add_f32_e32 v61, v157, v58
	v_add_f32_e32 v4, v159, v4
	v_mul_f32_e32 v66, 0x3fb8aa3b, v66
	v_mul_f32_e32 v67, 0x3fb8aa3b, v67
	v_mul_f32_e32 v69, 0x3fb8aa3b, v69
	v_mul_f32_e32 v63, 0x3fb8aa3b, v63
	v_mul_f32_e32 v59, 0x3fb8aa3b, v59
	v_mul_f32_e32 v60, 0x3fb8aa3b, v60
	v_mul_f32_e32 v61, 0x3fb8aa3b, v61
	v_mul_f32_e32 v4, 0x3fb8aa3b, v4
	v_exp_f32_e32 v66, v66
	v_exp_f32_e32 v69, v69
	v_exp_f32_e32 v59, v59
	v_exp_f32_e32 v61, v61
	v_exp_f32_e32 v4, v4
	v_exp_f32_e32 v60, v60
	v_exp_f32_e32 v62, v63
	v_exp_f32_e32 v63, v67
	v_cvt_pk_bf16_f32 v58, v4, v61
	v_cvt_pk_bf16_f32 v59, v60, v59
	v_cvt_pk_bf16_f32 v60, v62, v69
	v_cvt_pk_bf16_f32 v61, v63, v66
	ds_read_b64_tr_b16 v[206:207], v110
	ds_read_b64_tr_b16 v[208:209], v114
	ds_read_b64_tr_b16 v[210:211], v111
	ds_read_b64_tr_b16 v[212:213], v115
	ds_read_b64_tr_b16 v[214:215], v112
	ds_read_b64_tr_b16 v[216:217], v116
	ds_read_b64_tr_b16 v[218:219], v113
	ds_read_b64_tr_b16 v[220:221], v117
	ds_read_b64_tr_b16 v[222:223], v118
	ds_read_b64_tr_b16 v[224:225], v122
	ds_read_b64_tr_b16 v[226:227], v119
	ds_read_b64_tr_b16 v[228:229], v123
	ds_read_b64_tr_b16 v[230:231], v120
	ds_read_b64_tr_b16 v[232:233], v124
	ds_read_b64_tr_b16 v[234:235], v121
	s_waitcnt lgkmcnt(7)
	ds_read_b64_tr_b16 v[236:237], v125
	s_nop 0
	v_add_f32_e32 v156, v177, v180
	v_add_f32_e32 v4, v176, v156
	v_mfma_f32_16x16x32_bf16 v[54:57], v[206:209], v[58:61], v[54:57]
	v_add_f32_e32 v92, v175, v5
	v_add_f32_e32 v5, v174, v5
	v_mul_f32_e32 v4, 0x3fb8aa3b, v4
	v_mfma_f32_16x16x32_bf16 v[50:53], v[210:213], v[58:61], v[50:53]
	v_mul_f32_e32 v70, 0x3fb8aa3b, v92
	v_exp_f32_e32 v96, v70
	v_exp_f32_e32 v4, v4
	v_mfma_f32_16x16x32_bf16 v[46:49], v[214:217], v[58:61], v[46:49]
	v_add_f32_e32 v66, v173, v5
	v_mul_f32_e32 v97, 0x3fb8aa3b, v66
	v_add_f32_e32 v5, v172, v5
	v_mfma_f32_16x16x32_bf16 v[42:45], v[218:221], v[58:61], v[42:45]
	ds_read_b64_tr_b16 v[206:207], v126
	ds_read_b64_tr_b16 v[208:209], v130
	ds_read_b64_tr_b16 v[210:211], v127
	ds_read_b64_tr_b16 v[212:213], v131
	ds_read_b64_tr_b16 v[214:215], v128
	ds_read_b64_tr_b16 v[216:217], v132
	ds_read_b64_tr_b16 v[218:219], v129
	s_waitcnt lgkmcnt(7)
	ds_read_b64_tr_b16 v[220:221], v133
	s_nop 0
	s_nop 0
	v_mfma_f32_16x16x32_bf16 v[38:41], v[222:225], v[58:61], v[38:41]
	v_add_f32_e32 v92, v171, v5
	v_add_f32_e32 v5, v170, v5
	v_add_f32_e32 v5, v169, v5
	v_mul_f32_e32 v92, 0x3fb8aa3b, v92
	v_mul_f32_e32 v5, 0x3fb8aa3b, v5
	v_exp_f32_e32 v92, v92
	v_mfma_f32_16x16x32_bf16 v[30:33], v[230:233], v[58:61], v[30:33]
	v_exp_f32_e32 v5, v5
	v_exp_f32_e32 v66, v97
	v_mfma_f32_16x16x32_bf16 v[34:37], v[226:229], v[58:61], v[34:37]
	v_mfma_f32_16x16x32_bf16 v[26:29], v[234:237], v[58:61], v[26:29]
	v_cvt_pk_bf16_f32 v58, v5, v92
	v_cvt_pk_bf16_f32 v59, v66, v96
	v_cvt_pk_bf16_f32 v60, v4, v181
	v_cvt_pk_bf16_f32 v61, v178, v179
	ds_read_b64_tr_b16 v[222:223], v134
	ds_read_b64_tr_b16 v[224:225], v138
	ds_read_b64_tr_b16 v[226:227], v135
	ds_read_b64_tr_b16 v[228:229], v139
	ds_read_b64_tr_b16 v[230:231], v136
	ds_read_b64_tr_b16 v[232:233], v140
	ds_read_b64_tr_b16 v[234:235], v137
	s_waitcnt lgkmcnt(7)
	ds_read_b64_tr_b16 v[236:237], v141
	s_nop 0
	s_nop 1
	v_mfma_f32_16x16x32_bf16 v[54:57], v[206:209], v[58:61], v[54:57]
	v_mfma_f32_16x16x32_bf16 v[50:53], v[210:213], v[58:61], v[50:53]
	v_mfma_f32_16x16x32_bf16 v[46:49], v[214:217], v[58:61], v[46:49]
	v_mfma_f32_16x16x32_bf16 v[42:45], v[218:221], v[58:61], v[42:45]
	s_waitcnt lgkmcnt(0)
	s_nop 0
	s_nop 0
	v_mfma_f32_16x16x32_bf16 v[38:41], v[222:225], v[58:61], v[38:41]
	v_add_f32_e32 v93, v154, v155
	v_cmp_gt_f32_e32 vcc, s55, v93
	s_cmp_eq_u64 vcc, exec
	v_mfma_f32_16x16x32_bf16 v[34:37], v[226:229], v[58:61], v[34:37]
	s_cselect_b64 s[0:1], -1, 0
	s_mov_b64 s[64:65], s[0:1]
	v_mfma_f32_16x16x32_bf16 v[30:33], v[230:233], v[58:61], v[30:33]
	v_mfma_f32_16x16x32_bf16 v[26:29], v[234:237], v[58:61], v[26:29]
	s_and_saveexec_b64 s[18:19], s[10:11]
	s_cbranch_execz .LBB0_1905
	s_branch .LBB0_1913
